# attention epilogue: 8 dwordx2 row stores per lane widened to 4 dwordx4 with v_permlane32_swap pairs (lever 7.3), same bytes
# speedup vs baseline: 1.0102x; 1.0102x over previous
; __device__ __forceinline__ unsigned pk2(float lo, float hi) { f32x2 v = {lo, hi}; bf16x2_t b = __builtin_convertvector(v, bf16x2_t); return __builtin_bit_cast(unsigned, b); }
;     ...
;         const float lt = l_run + __shfl_xor(l_run, 32); const float inv = 1.0f / lt;
;         bf16_t* op = OB + (size_t)(b * SEQ + qrow) * 1024 + head * 64 + 4 * hi;
; #pragma unroll
;         for (int g = 0; g < 4; ++g) {
;             u32x2 w0, w1; w0.x = pk2(o0[4 * g] * inv, o0[4 * g + 1] * inv); w0.y = pk2(o0[4 * g + 2] * inv, o0[4 * g + 3] * inv);
;             w1.x = pk2(o1[4 * g] * inv, o1[4 * g + 1] * inv); w1.y = pk2(o1[4 * g + 2] * inv, o1[4 * g + 3] * inv);
;             *(u32x2*)(op + 8 * g) = w0; *(u32x2*)(op + 32 + 8 * g) = w1;
;         }
.LBB0_502:
	s_mul_i32 s8, s59, 0x2200
	v_add_u32_e32 v4, s8, v174
	v_add_u32_e32 v12, 0x4800, v4
	ds_read2_b64 v[0:3], v12 offset1:2
	v_bfi_b32 v135, s54, v135, v135
	v_add_u32_e32 v48, 0x5800, v4
	ds_read2_b64 v[4:7], v48 offset0:36 offset1:38
	v_bfi_b32 v131, s54, v131, v131
	ds_bpermute_b32 v52, v176, v165
	v_bfi_b32 v127, s54, v127, v127
	v_bfi_b32 v123, s54, v123, v123
	s_lshl_b32 s8, s56, 1
	s_waitcnt lgkmcnt(2)
	v_mfma_f32_32x32x16_bf16 v[16:31], v[0:3], v[132:135], v[16:31]
	ds_read2_b64 v[0:3], v48 offset0:32 offset1:34
	v_mov_b32_e32 v167, v147
	s_add_i32 s55, s55, s3
	s_add_i32 s44, s44, s45
	s_cmpk_gt_i32 s55, 0xfff
	s_waitcnt lgkmcnt(0)
	v_mfma_f32_32x32x16_bf16 v[32:47], v[0:3], v[132:135], v[32:47]
	ds_read2_b64 v[0:3], v12 offset0:4 offset1:6
	s_waitcnt lgkmcnt(0)
	v_mfma_f32_32x32x16_bf16 v[16:31], v[0:3], v[128:131], v[16:31]
	ds_read2_b64 v[0:3], v12 offset0:8 offset1:10
	ds_read2_b64 v[8:11], v48 offset0:40 offset1:42
	ds_read2_b64 v[12:15], v12 offset0:12 offset1:14
	ds_read2_b64 v[48:51], v48 offset0:44 offset1:46
	s_waitcnt lgkmcnt(0)
	s_barrier
	v_mfma_f32_32x32x16_bf16 v[32:47], v[4:7], v[128:131], v[32:47]
	v_add_f32_e32 v4, v165, v52
	v_div_scale_f32 v5, s[22:23], v4, v4, 1.0
	v_rcp_f32_e32 v6, v5
	v_mfma_f32_32x32x16_bf16 v[16:31], v[0:3], v[124:127], v[16:31]
	v_fma_f32 v0, -v5, v6, 1.0
	v_fmac_f32_e32 v6, v0, v6
	v_div_scale_f32 v0, vcc, 1.0, v4, 1.0
	v_mul_f32_e32 v1, v0, v6
	v_fma_f32 v2, -v5, v1, v0
	v_fmac_f32_e32 v1, v2, v6
	v_mfma_f32_32x32x16_bf16 v[32:47], v[8:11], v[124:127], v[32:47]
	v_fma_f32 v0, -v5, v1, v0
	v_div_fmas_f32 v0, v0, v6, v1
	v_div_fixup_f32 v0, v0, v4, 1.0
	v_lshlrev_b64 v[2:3], 11, v[170:171]
	v_lshl_add_u64 v[2:3], s[6:7], 0, v[2:3]
	v_lshl_add_u64 v[2:3], v[2:3], 0, s[8:9]
	v_lshl_add_u64 v[2:3], v[2:3], 0, v[166:167]
	v_mfma_f32_32x32x16_bf16 v[16:31], v[12:15], v[120:123], v[16:31]
	v_mfma_f32_32x32x16_bf16 v[32:47], v[48:51], v[120:123], v[32:47]
	s_nop 10
	v_and_b32_e32 v52, 32, v152
	v_lshrrev_b32_e32 v52, 2, v52
	v_mov_b32_e32 v53, 0
	v_lshl_add_u64 v[2:3], v[2:3], 0, v[52:53]
	v_pk_mul_f32 v[4:5], v[16:17], v[0:1] op_sel_hi:[1,0]
	v_pk_mul_f32 v[6:7], v[18:19], v[0:1] op_sel_hi:[1,0]
	v_pk_mul_f32 v[8:9], v[20:21], v[0:1] op_sel_hi:[1,0]
	v_pk_mul_f32 v[10:11], v[22:23], v[0:1] op_sel_hi:[1,0]
	v_cvt_pk_bf16_f32 v4, v4, v5
	v_cvt_pk_bf16_f32 v5, v6, v7
	v_cvt_pk_bf16_f32 v6, v8, v9
	v_cvt_pk_bf16_f32 v7, v10, v11
	v_pk_mul_f32 v[8:9], v[24:25], v[0:1] op_sel_hi:[1,0]
	v_pk_mul_f32 v[10:11], v[26:27], v[0:1] op_sel_hi:[1,0]
	v_pk_mul_f32 v[12:13], v[28:29], v[0:1] op_sel_hi:[1,0]
	v_pk_mul_f32 v[14:15], v[30:31], v[0:1] op_sel_hi:[1,0]
	v_permlane32_swap_b32 v4, v6
	v_permlane32_swap_b32 v5, v7
	global_store_dwordx4 v[2:3], v[4:7], off
	v_cvt_pk_bf16_f32 v8, v8, v9
	v_cvt_pk_bf16_f32 v9, v10, v11
	v_cvt_pk_bf16_f32 v10, v12, v13
	v_cvt_pk_bf16_f32 v11, v14, v15
	v_pk_mul_f32 v[12:13], v[32:33], v[0:1] op_sel_hi:[1,0]
	v_pk_mul_f32 v[14:15], v[34:35], v[0:1] op_sel_hi:[1,0]
	v_pk_mul_f32 v[48:49], v[36:37], v[0:1] op_sel_hi:[1,0]
	v_pk_mul_f32 v[50:51], v[38:39], v[0:1] op_sel_hi:[1,0]
	v_permlane32_swap_b32 v8, v10
	v_permlane32_swap_b32 v9, v11
	global_store_dwordx4 v[2:3], v[8:11], off offset:32
	v_cvt_pk_bf16_f32 v12, v12, v13
	v_cvt_pk_bf16_f32 v13, v14, v15
	v_cvt_pk_bf16_f32 v14, v48, v49
	v_cvt_pk_bf16_f32 v15, v50, v51
	v_pk_mul_f32 v[48:49], v[40:41], v[0:1] op_sel_hi:[1,0]
	v_pk_mul_f32 v[50:51], v[42:43], v[0:1] op_sel_hi:[1,0]
	v_pk_mul_f32 v[52:53], v[44:45], v[0:1] op_sel_hi:[1,0]
	v_pk_mul_f32 v[54:55], v[46:47], v[0:1] op_sel_hi:[1,0]
	v_permlane32_swap_b32 v12, v14
	v_permlane32_swap_b32 v13, v15
	global_store_dwordx4 v[2:3], v[12:15], off offset:64
	v_cvt_pk_bf16_f32 v48, v48, v49
	v_cvt_pk_bf16_f32 v49, v50, v51
	v_cvt_pk_bf16_f32 v50, v52, v53
	v_cvt_pk_bf16_f32 v51, v54, v55
	s_nop 1
	v_permlane32_swap_b32 v48, v50
	v_permlane32_swap_b32 v49, v51
	global_store_dwordx4 v[2:3], v[48:51], off offset:96
	s_cbranch_scc1 .LBB0_525
